# v16 with w_in_b rank classes 11/10/9/9/8/8/7/2 (slowest 32 WGs convert only 2 tiles)
# speedup vs baseline: 1.0006x; 1.0001x over previous
; #define LAS __attribute__((address_space(3)))
; template <bool REMAP = false>
; __device__ __forceinline__ void transpose_convert(LAS unsigned char* lds, const float* src, bf16_t* dst, int K, int N, int G, int bid) {
;     LAS float* tile = (LAS float*)lds;
;     const int tid = threadIdx.x, ntn = N / 64, ntiles = (K / 128) * ntn;
;     const int r0 = tid >> 4, c4 = tid & 15;
;     f32x4 v[4];
;     if (bid < ntiles) { const int k0 = (bid / ntn) * 128, n0 = (bid % ntn) * 64;
; #pragma unroll
;         for (int i = 0; i < 4; ++i) v[i] = __builtin_nontemporal_load((const f32x4*)(src + (size_t)(k0 + r0 + 32 * i) * N + n0 + c4 * 4)); }
;     for (int t = bid; t < ntiles; t += G) {
;         const int k0 = (t / ntn) * 128, n0 = (t % ntn) * 64;
; __global__ void __launch_bounds__(NTHREADS, 2) mk_fwd(Params P) {
;     ...
;         transpose_convert(lds, P.w_in_b, WINB, 2048, 8192, G, bid);
.LBB0_416:
	s_cmp_lt_i32 s42, 6
	s_cselect_b64 s[0:1], -1, 0
	s_cmp_gt_i32 s43, 5
	s_cselect_b64 s[4:5], -1, 0
	s_and_b64 s[0:1], s[0:1], s[4:5]
	s_andn2_b64 vcc, exec, s[0:1]
	s_cbranch_vccnz .LBB0_448
	v_and_b32_e32 v20, 15, v164
	v_mov_b32_e32 v46, 0x20008
	ds_read_b32 v48, v46
	s_waitcnt lgkmcnt(0)
	v_readfirstlane_b32 s99, v48
	s_and_b32 s99, s99, 0xff
	s_lshr_b32 s3, s99, 5
	s_and_b32 s4, s99, 31
	s_mov_b32 s100, 11
	s_mov_b32 s5, 0
	s_cmp_lt_u32 s3, 1
	s_cbranch_scc1 .Lrk5_done
	s_mov_b32 s100, 10
	s_movk_i32 s5, 352
	s_cmp_lt_u32 s3, 2
	s_cbranch_scc1 .Lrk5_done
	s_mov_b32 s100, 9
	s_movk_i32 s5, 672
	s_cmp_lt_u32 s3, 3
	s_cbranch_scc1 .Lrk5_done
	s_mov_b32 s100, 9
	s_movk_i32 s5, 960
	s_cmp_lt_u32 s3, 4
	s_cbranch_scc1 .Lrk5_done
	s_mov_b32 s100, 8
	s_movk_i32 s5, 1248
	s_cmp_lt_u32 s3, 5
	s_cbranch_scc1 .Lrk5_done
	s_mov_b32 s100, 8
	s_movk_i32 s5, 1504
	s_cmp_lt_u32 s3, 6
	s_cbranch_scc1 .Lrk5_done
	s_mov_b32 s100, 7
	s_movk_i32 s5, 1760
	s_cmp_lt_u32 s3, 7
	s_cbranch_scc1 .Lrk5_done
	s_mov_b32 s100, 2
	s_movk_i32 s5, 1984
